# grid barrier poll loops: s_sleep 8 -> s_sleep 4 between polls of the cross-XCD arrival counter
# baseline (speedup 1.0000x reference)
.LBB0_107:
	s_and_b32 s22, s26, 0xff
	s_mov_b64 s[20:21], -1
	s_cmp_lg_u32 s22, 0
	s_mov_b64 s[24:25], -1
	s_sleep 4
	s_cbranch_scc1 .LBB0_110
	global_load_dword v2, v0, s[12:13] sc1
	s_waitcnt vmcnt(0)
	v_cmp_eq_u32_e32 vcc, 0, v2
	s_cbranch_vccnz .LBB0_112
	s_mov_b64 s[24:25], 0
	s_mov_b64 s[22:23], -1

.LBB0_124:
	s_and_b32 s20, s26, 0xff
	s_cmp_lg_u32 s20, 0
	s_mov_b64 s[22:23], -1
	s_sleep 4
	s_cbranch_scc1 .LBB0_127
	global_load_dword v1, v0, s[12:13] sc1
	s_waitcnt vmcnt(0)
	v_cmp_eq_u32_e32 vcc, 0, v1
	s_cbranch_vccnz .LBB0_129
	s_mov_b64 s[22:23], 0
	s_mov_b64 s[20:21], -1

.LBB0_223:
	s_and_b32 s7, s6, 0xff
	s_mov_b64 s[24:25], -1
	s_cmp_lg_u32 s7, 0
	s_mov_b64 s[30:31], -1
	s_sleep 4
	s_cbranch_scc1 .LBB0_226
	global_load_dword v2, v0, s[16:17] sc1
	s_waitcnt vmcnt(0)
	v_cmp_eq_u32_e32 vcc, 0, v2
	s_cbranch_vccnz .LBB0_228
	s_mov_b64 s[30:31], 0
	s_mov_b64 s[26:27], -1

.LBB0_240:
	s_and_b32 s7, s6, 0xff
	s_cmp_lg_u32 s7, 0
	s_mov_b64 s[26:27], -1
	s_sleep 4
	s_cbranch_scc1 .LBB0_243
	global_load_dword v1, v0, s[16:17] sc1
	s_waitcnt vmcnt(0)
	v_cmp_eq_u32_e32 vcc, 0, v1
	s_cbranch_vccnz .LBB0_245
	s_mov_b64 s[26:27], 0
	s_mov_b64 s[24:25], -1

.LBB0_288:
	s_and_b32 s26, s34, 0xff
	s_mov_b64 s[24:25], -1
	s_cmp_lg_u32 s26, 0
	s_mov_b64 s[30:31], -1
	s_sleep 4
	s_cbranch_scc1 .LBB0_291
	global_load_dword v2, v0, s[16:17] sc1
	s_waitcnt vmcnt(0)
	v_cmp_eq_u32_e32 vcc, 0, v2
	s_cbranch_vccnz .LBB0_293
	s_mov_b64 s[30:31], 0
	s_mov_b64 s[26:27], -1

.LBB0_305:
	s_and_b32 s24, s34, 0xff
	s_cmp_lg_u32 s24, 0
	s_mov_b64 s[26:27], -1
	s_sleep 4
	s_cbranch_scc1 .LBB0_308
	global_load_dword v1, v0, s[16:17] sc1
	s_waitcnt vmcnt(0)
	v_cmp_eq_u32_e32 vcc, 0, v1
	s_cbranch_vccnz .LBB0_310
	s_mov_b64 s[26:27], 0
	s_mov_b64 s[24:25], -1

.LBB0_486:
	s_and_b32 s7, s6, 0xff
	s_cmp_lg_u32 s7, 0
	s_mov_b64 s[30:31], -1
	s_sleep 4
	s_cbranch_scc1 .LBB0_489
	global_load_dword v1, v0, s[18:19] sc1
	s_waitcnt vmcnt(0)
	v_cmp_eq_u32_e32 vcc, 0, v1
	s_cbranch_vccnz .LBB0_491
	s_mov_b64 s[30:31], 0
	s_mov_b64 s[26:27], -1

.LBB0_997:
	s_and_b32 s24, s30, 0xff
	s_mov_b64 s[22:23], -1
	s_cmp_lg_u32 s24, 0
	s_mov_b64 s[26:27], -1
	s_sleep 4
	s_cbranch_scc1 .LBB0_1000
	global_load_dword v2, v0, s[14:15] sc1
	s_waitcnt vmcnt(0)
	v_cmp_eq_u32_e32 vcc, 0, v2
	s_cbranch_vccnz .LBB0_1002
	s_mov_b64 s[26:27], 0
	s_mov_b64 s[24:25], -1

.LBB0_1014:
	s_and_b32 s22, s30, 0xff
	s_cmp_lg_u32 s22, 0
	s_mov_b64 s[24:25], -1
	s_sleep 4
	s_cbranch_scc1 .LBB0_1017
	global_load_dword v1, v0, s[14:15] sc1
	s_waitcnt vmcnt(0)
	v_cmp_eq_u32_e32 vcc, 0, v1
	s_cbranch_vccnz .LBB0_1019
	s_mov_b64 s[24:25], 0
	s_mov_b64 s[22:23], -1

.LBB0_1272:
	s_and_b32 s22, s26, 0xff
	s_mov_b64 s[20:21], -1
	s_cmp_lg_u32 s22, 0
	s_mov_b64 s[24:25], -1
	s_sleep 4
	s_cbranch_scc1 .LBB0_1275
	global_load_dword v18, v16, s[12:13] sc1
	s_waitcnt vmcnt(0)
	v_cmp_eq_u32_e32 vcc, 0, v18
	s_cbranch_vccnz .LBB0_1277
	s_mov_b64 s[24:25], 0
	s_mov_b64 s[22:23], -1

.LBB0_1289:
	s_and_b32 s20, s26, 0xff
	s_cmp_lg_u32 s20, 0
	s_mov_b64 s[22:23], -1
	s_sleep 4
	s_cbranch_scc1 .LBB0_1292
	global_load_dword v17, v16, s[12:13] sc1
	s_waitcnt vmcnt(0)
	v_cmp_eq_u32_e32 vcc, 0, v17
	s_cbranch_vccnz .LBB0_1294
	s_mov_b64 s[22:23], 0
	s_mov_b64 s[20:21], -1
